# row-tile barriers: seams 3-4, 5-6, 11-12, 13-14, 16-17 synchronise only the four CUs owning the same 256-row tile (one arrival counter per row tile) instead of the XCD-wide barrier
# baseline (speedup 1.0000x reference)
.LBB0_595:
	s_cmp_eq_u32 s100, 0
	s_cbranch_scc1 .Lbar_slow
	s_lshl_b32 s4, 1, s73
	s_and_b32 s4, s4, 0x12828
	s_cmp_eq_u32 s4, 0
	s_cbranch_scc1 .Lbar_slow
	s_mov_b32 s2, 1
	s_cmp_ge_u32 s73, 5
	s_addc_u32 s2, s2, 0
	s_cmp_ge_u32 s73, 11
	s_addc_u32 s2, s2, 0
	s_cmp_ge_u32 s73, 13
	s_addc_u32 s2, s2, 0
	s_cmp_ge_u32 s73, 16
	s_addc_u32 s2, s2, 0
	s_lshl_b32 s2, s2, 2
	s_and_b32 s36, s92, 7
	s_lshl_b32 s36, s36, 3
	s_lshr_b32 s37, s92, 3
	s_and_b32 s4, s37, 7
	s_add_i32 s4, s36, s4
	s_lshr_b32 s37, s92, 5
	s_add_i32 s37, s36, s37
	s_cmp_eq_u32 s73, 16
	s_cselect_b32 s37, s37, s4
	s_mov_b32 s36, s4
	s_lshr_b32 s5, s36, 4
	s_and_b32 s4, s36, 15
	s_lshl_b32 s4, s4, 8
	s_lshl_b32 s36, s5, 6
	s_add_i32 s36, s36, 0x240
	s_cmp_eq_u32 s5, 3
	s_cselect_b32 s36, 0x12c0, s36
	s_add_i32 s36, s36, s4
	s_lshr_b32 s5, s37, 4
	s_and_b32 s4, s37, 15
	s_lshl_b32 s4, s4, 8
	s_lshl_b32 s37, s5, 6
	s_add_i32 s37, s37, 0x240
	s_cmp_eq_u32 s5, 3
	s_cselect_b32 s37, 0x12c0, s37
	s_add_i32 s37, s37, s4
	v_readlane_b32 s4, v253, 3
	v_readlane_b32 s5, v253, 4
	v_mov_b32_e32 v1, s36
	v_mov_b32_e32 v4, s37
	v_mov_b32_e32 v3, 1
	s_nop 2
	global_atomic_add v1, v3, s[4:5]
	buffer_inv sc1
	s_mov_b32 s36, 0
.Lbar_rtspin:
	global_load_dword v3, v4, s[4:5] sc1
	s_waitcnt vmcnt(0)
	v_cmp_le_u32_e32 vcc, s2, v3
	s_cbranch_vccnz .LBB0_24
	s_sleep 1
	s_add_i32 s36, s36, 1
	s_cmp_lt_u32 s36, 0x40000
	s_cbranch_scc1 .Lbar_rtspin
	s_branch .LBB0_24
